# DA loop: bias-side switch detected with scalar compares (per-tile bias LDS reads and vector compare removed), +0x4400 staging offset folded into an SGPR
# baseline (speedup 1.0000x reference)
; __device__ __forceinline__ void da_unit(LAS unsigned char* lds, const bf16_t* __restrict__ proj, bf16_t* __restrict__ y, int unit,
;                                         const float* __restrict__ t5, float lam, float one_m_li, const float* __restrict__ subg) {
;     ...
;         const int j1 = j + 1;
;         const bool near1 = (64 * j1 + 63 >= qblk - 128) && (64 * j1 <= qblk + 255);
;         const float bc1 = tbl[(64 * j1 > qblk) ? 256 : 0]; const int dtoff1 = (64 * j1 > qblk) ? DA_DR_OFF : DA_DL_OFF;
;         DA_STEP(sa, sb, pp0, pp1, pc0, pc1, lds + bprev, 1, lds + bcur, 1, j * 64, lds + bcur, 0);
.LBB0_162:
	s_sub_i32 s85, s81, 64
	s_cmp_gt_u32 s85, s97
	s_cselect_b64 s[78:79], -1, 0
	s_and_b64 s[86:87], s[78:79], exec
	s_mov_b32 s84, s82
	s_mov_b32 s82, s7
	s_cselect_b32 s7, 0x400, 0
	s_add_i32 s7, s7, 0
	s_add_i32 s7, s7, 0x18c00
	s_add_i32 s7, s81, 0xffffff80
	s_cmp_gt_i32 s7, s40
	s_cselect_b64 s[88:89], -1, 0
	s_add_i32 s86, s80, s76
	s_sub_i32 s9, s86, 31
	s_cmpk_gt_i32 s9, 0x7f
	s_cselect_b64 s[90:91], -1, 0
	s_or_b64 s[88:89], s[88:89], s[90:91]
	s_and_b64 vcc, exec, s[88:89]
	s_cbranch_vccnz .LBB0_164
	v_add_u32_e32 v80, s6, v189
	v_add_u32_e32 v88, 0x500, v80
	v_add_u32_e32 v90, 0x508, v80
	v_add_u32_e32 v92, 0x520, v80
	v_add_u32_e32 v94, 0x528, v80
	v_add_u32_e32 v81, 0x540, v80
	v_add_u32_e32 v82, 0x548, v80
	v_add_u32_e32 v84, 0x560, v80
	v_add_u32_e32 v86, 0x568, v80
	ds_read2_b32 v[80:81], v81 offset1:1
	ds_read2_b32 v[82:83], v82 offset1:1
	ds_read2_b32 v[84:85], v84 offset1:1
	ds_read2_b32 v[86:87], v86 offset1:1
	ds_read2_b32 v[88:89], v88 offset1:1
	ds_read2_b32 v[90:91], v90 offset1:1
	ds_read2_b32 v[92:93], v92 offset1:1
	ds_read2_b32 v[94:95], v94 offset1:1
	s_waitcnt lgkmcnt(4)
	v_pk_add_f32 v[78:79], v[78:79], v[86:87]
	v_pk_add_f32 v[76:77], v[76:77], v[84:85]
	v_pk_add_f32 v[74:75], v[74:75], v[82:83]
	v_pk_add_f32 v[72:73], v[72:73], v[80:81]
	s_waitcnt lgkmcnt(0)
	v_pk_add_f32 v[70:71], v[70:71], v[94:95]
	v_pk_add_f32 v[68:69], v[68:69], v[92:93]
	v_pk_add_f32 v[66:67], v[66:67], v[90:91]
	v_pk_add_f32 v[64:65], v[64:65], v[88:89]
.LBB0_164:
	s_add_i32 s8, s8, 0
	v_add_u32_e32 v80, s8, v188
	v_xor_b32_e32 v84, 0x60, v80
	v_xor_b32_e32 v92, 32, v80
	ds_read_b128 v[80:83], v84
	ds_read_b128 v[84:87], v84 offset:8192
	ds_read_b128 v[88:91], v92 offset:4096
	ds_read_b128 v[92:95], v92 offset:12288
	s_waitcnt lgkmcnt(7)
	v_mfma_f32_32x32x16_bf16 v[48:63], v[140:143], v[148:151], v[48:63]
	v_exp_f32_e32 v156, v64
	v_exp_f32_e32 v157, v65
	s_waitcnt lgkmcnt(5)
	v_mfma_f32_32x32x16_bf16 v[32:47], v[136:139], v[148:151], v[32:47]
	v_exp_f32_e32 v158, v66
	v_exp_f32_e32 v159, v67
	v_add_f32_e32 v253, v157, v156
	v_mfma_f32_32x32x16_bf16 v[16:31], v[132:135], v[148:151], v[16:31]
	v_exp_f32_e32 v160, v68
	v_exp_f32_e32 v161, v69
	v_add_f32_e32 v253, v158, v253
	v_add_f32_e32 v253, v159, v253
	s_waitcnt lgkmcnt(4)
	v_mfma_f32_32x32x16_bf16 v[0:15], v[128:131], v[148:151], v[0:15]
	s_add_i32 s87, s82, 0
	s_add_i32 s8, s36, s87
	v_add3_u32 v128, s8, v186, v174
	ds_read_b128 v[148:151], v128 offset:8704
	ds_read_b128 v[192:195], v128 offset:8736
	ds_read_b128 v[198:201], v128 offset:8768
	ds_read_b128 v[224:227], v128 offset:8800
	v_exp_f32_e32 v162, v70
	v_exp_f32_e32 v163, v71
	v_add_f32_e32 v253, v160, v253
	v_add_f32_e32 v253, v161, v253
	s_waitcnt lgkmcnt(7)
	v_mfma_f32_32x32x16_bf16 v[48:63], v[80:83], v[144:147], v[48:63]
	v_add_u32_e32 v190, s87, v188
	v_xor_b32_e32 v191, 64, v190
	ds_read_b128 v[128:131], v190
	ds_read_b128 v[132:135], v191 offset:4096
	ds_read_b128 v[136:139], v190 offset:8192
	ds_read_b128 v[140:143], v191 offset:12288
	v_exp_f32_e32 v214, v72
	v_exp_f32_e32 v215, v73
	v_add_f32_e32 v253, v162, v253
	v_add_f32_e32 v253, v163, v253
	s_waitcnt lgkmcnt(9)
	v_mfma_f32_32x32x16_bf16 v[32:47], v[88:91], v[144:147], v[32:47]
	v_exp_f32_e32 v216, v74
	v_exp_f32_e32 v217, v75
	v_add_f32_e32 v253, v214, v253
	v_add_f32_e32 v253, v215, v253
	v_mfma_f32_32x32x16_bf16 v[16:31], v[84:87], v[144:147], v[16:31]
	v_exp_f32_e32 v218, v76
	v_exp_f32_e32 v219, v77
	v_add_f32_e32 v253, v216, v253
	v_add_f32_e32 v253, v217, v253
	s_waitcnt lgkmcnt(8)
	v_mfma_f32_32x32x16_bf16 v[0:15], v[92:95], v[144:147], v[0:15]
	v_exp_f32_e32 v220, v78
	v_exp_f32_e32 v221, v79
	v_add_f32_e32 v253, v218, v253
	v_add_f32_e32 v253, v219, v253
	s_waitcnt lgkmcnt(7)
	v_mfma_f32_32x32x16_bf16 v[80:95], v[148:151], v[104:107], v[232:247]
	v_add_f32_e32 v253, v220, v253
	v_cvt_pk_bf16_f32 v144, v156, v157
	v_cvt_pk_bf16_f32 v145, v158, v159
	s_waitcnt lgkmcnt(6)
	v_mfma_f32_32x32x16_bf16 v[80:95], v[192:195], v[96:99], v[80:95]
	v_cvt_pk_bf16_f32 v146, v160, v161
	v_cvt_pk_bf16_f32 v147, v162, v163
	s_waitcnt lgkmcnt(5)
	v_mfma_f32_32x32x16_bf16 v[80:95], v[198:201], v[100:103], v[80:95]
	v_cvt_pk_bf16_f32 v148, v214, v215
	v_cvt_pk_bf16_f32 v149, v216, v217
	s_waitcnt lgkmcnt(4)
	v_mfma_f32_32x32x16_bf16 v[80:95], v[224:227], v[108:111], v[80:95]
	v_add_f32_e32 v192, v221, v253
	v_cvt_pk_bf16_f32 v150, v218, v219
	v_cvt_pk_bf16_f32 v151, v220, v221
	v_cmp_ngt_f32_e32 vcc, s68, v192
	s_cbranch_vccz .LBB0_167
	v_max3_f32 v250, v64, v65, v66
	v_max3_f32 v251, v67, v68, v69
	v_max3_f32 v250, v250, v70, v71
	v_max3_f32 v251, v251, v72, v73
	v_max3_f32 v250, v250, v74, v75
	v_max3_f32 v251, v251, v76, v77
	v_max3_f32 v250, v250, v78, v79
	v_max_f32_e32 v250, v250, v251
	v_mov_b32_e32 v251, v250
	s_nop 1
	v_permlane32_swap_b32_e32 v250, v251
	v_max_f32_e32 v250, v250, v251
	v_cmp_lt_f32_e32 vcc, v154, v250
	s_cbranch_vccz .LBB0_167
; #define DA_LOAD(j) do { const bf16_t* t_ = kvbase + (size_t)(j) * 64 * 4096; kreg0 = *(const u32x4*)(t_ + kgo); kreg1 = *(const u32x4*)(t_ + (kgo + 32u * 4096u)); vreg0 = *(const u32x4*)(t_ + vgo); vreg1 = *(const u32x4*)(t_ + (vgo + 4096u)); } while (0)
; __device__ __forceinline__ void da_unit(LAS unsigned char* lds, const bf16_t* __restrict__ proj, bf16_t* __restrict__ y, int unit,
;                                         const float* __restrict__ t5, float lam, float one_m_li, const float* __restrict__ subg) {
;     ...
; #pragma unroll 2
;     for (int j = 0; j < 64; ++j) {
;         const int j1 = j + 1;
;         const bool near1 = (64 * j1 + 63 >= qblk - 128) && (64 * j1 <= qblk + 255);
;         const float bc1 = tbl[(64 * j1 > qblk) ? 256 : 0]; const int dtoff1 = (64 * j1 > qblk) ? DA_DR_OFF : DA_DL_OFF;
;         DA_STEP(sa, sb, pp0, pp1, pc0, pc1, lds + bprev, 1, lds + bcur, 1, j * 64, lds + bcur, 0);
;         __syncthreads();
;         DA_STORE(lds + bnn); { const int jl = j + 3 < 64 ? j + 3 : 63; DA_LOAD(jl); }
	s_nop 1
	v_cndmask_b32_e32 v250, 0, v250, vcc
	v_sub_f32_e32 v251, 0, v250
	v_exp_f32_e32 v251, v251
	s_nop 0
	v_mul_f32_e32 v0, v251, v0
	v_mul_f32_e32 v1, v251, v1
	v_mul_f32_e32 v2, v251, v2
	v_mul_f32_e32 v3, v251, v3
	v_mul_f32_e32 v4, v251, v4
	v_mul_f32_e32 v5, v251, v5
	v_mul_f32_e32 v6, v251, v6
	v_mul_f32_e32 v7, v251, v7
	v_mul_f32_e32 v8, v251, v8
	v_mul_f32_e32 v9, v251, v9
	v_mul_f32_e32 v10, v251, v10
	v_mul_f32_e32 v11, v251, v11
	v_mul_f32_e32 v12, v251, v12
	v_mul_f32_e32 v13, v251, v13
	v_mul_f32_e32 v14, v251, v14
	v_mul_f32_e32 v15, v251, v15
	v_mul_f32_e32 v16, v251, v16
	v_mul_f32_e32 v17, v251, v17
	v_mul_f32_e32 v18, v251, v18
	v_mul_f32_e32 v19, v251, v19
	v_mul_f32_e32 v20, v251, v20
	v_mul_f32_e32 v21, v251, v21
	v_mul_f32_e32 v22, v251, v22
	v_mul_f32_e32 v23, v251, v23
	v_mul_f32_e32 v24, v251, v24
	v_mul_f32_e32 v25, v251, v25
	v_mul_f32_e32 v26, v251, v26
	v_mul_f32_e32 v27, v251, v27
	v_mul_f32_e32 v28, v251, v28
	v_mul_f32_e32 v29, v251, v29
	v_mul_f32_e32 v30, v251, v30
	v_mul_f32_e32 v31, v251, v31
	v_mul_f32_e32 v32, v251, v32
	v_mul_f32_e32 v33, v251, v33
	v_mul_f32_e32 v34, v251, v34
	v_mul_f32_e32 v35, v251, v35
	v_mul_f32_e32 v36, v251, v36
	v_mul_f32_e32 v37, v251, v37
	v_mul_f32_e32 v38, v251, v38
	v_mul_f32_e32 v39, v251, v39
	v_mul_f32_e32 v40, v251, v40
	v_mul_f32_e32 v41, v251, v41
	v_mul_f32_e32 v42, v251, v42
	v_mul_f32_e32 v43, v251, v43
	v_mul_f32_e32 v44, v251, v44
	v_mul_f32_e32 v45, v251, v45
	v_mul_f32_e32 v46, v251, v46
	v_mul_f32_e32 v47, v251, v47
	v_mul_f32_e32 v48, v251, v48
	v_mul_f32_e32 v49, v251, v49
	v_mul_f32_e32 v50, v251, v50
	v_mul_f32_e32 v51, v251, v51
	v_mul_f32_e32 v52, v251, v52
	v_mul_f32_e32 v53, v251, v53
	v_mul_f32_e32 v54, v251, v54
	v_mul_f32_e32 v55, v251, v55
	v_mul_f32_e32 v56, v251, v56
	v_mul_f32_e32 v57, v251, v57
	v_mul_f32_e32 v58, v251, v58
	v_mul_f32_e32 v59, v251, v59
	v_mul_f32_e32 v60, v251, v60
	v_mul_f32_e32 v61, v251, v61
	v_mul_f32_e32 v62, v251, v62
	v_mul_f32_e32 v63, v251, v63
	v_mul_f32_e32 v178, v251, v178
	v_sub_f32_e32 v64, v64, v250
	v_sub_f32_e32 v65, v65, v250
	v_sub_f32_e32 v66, v66, v250
	v_sub_f32_e32 v67, v67, v250
	v_sub_f32_e32 v68, v68, v250
	v_sub_f32_e32 v69, v69, v250
	v_sub_f32_e32 v70, v70, v250
	v_sub_f32_e32 v71, v71, v250
	v_sub_f32_e32 v72, v72, v250
	v_sub_f32_e32 v73, v73, v250
	v_sub_f32_e32 v74, v74, v250
	v_sub_f32_e32 v75, v75, v250
	v_sub_f32_e32 v76, v76, v250
	v_sub_f32_e32 v77, v77, v250
	v_sub_f32_e32 v78, v78, v250
	v_sub_f32_e32 v79, v79, v250
	v_sub_f32_e32 v80, v80, v250
	v_sub_f32_e32 v81, v81, v250
	v_sub_f32_e32 v82, v82, v250
	v_sub_f32_e32 v83, v83, v250
	v_sub_f32_e32 v84, v84, v250
	v_sub_f32_e32 v85, v85, v250
	v_sub_f32_e32 v86, v86, v250
	v_sub_f32_e32 v87, v87, v250
	v_sub_f32_e32 v88, v88, v250
	v_sub_f32_e32 v89, v89, v250
	v_sub_f32_e32 v90, v90, v250
	v_sub_f32_e32 v91, v91, v250
	v_sub_f32_e32 v92, v92, v250
	v_sub_f32_e32 v93, v93, v250
	v_sub_f32_e32 v94, v94, v250
	v_sub_f32_e32 v95, v95, v250
	v_sub_f32_e32 v232, v232, v250
	v_sub_f32_e32 v233, v233, v250
	v_sub_f32_e32 v234, v234, v250
	v_sub_f32_e32 v235, v235, v250
	v_sub_f32_e32 v236, v236, v250
	v_sub_f32_e32 v237, v237, v250
	v_sub_f32_e32 v238, v238, v250
	v_sub_f32_e32 v239, v239, v250
	v_sub_f32_e32 v240, v240, v250
	v_sub_f32_e32 v241, v241, v250
	v_sub_f32_e32 v242, v242, v250
	v_sub_f32_e32 v243, v243, v250
	v_sub_f32_e32 v244, v244, v250
	v_sub_f32_e32 v245, v245, v250
	v_sub_f32_e32 v246, v246, v250
	v_sub_f32_e32 v247, v247, v250
	v_exp_f32_e32 v156, v64
	v_exp_f32_e32 v157, v65
	v_exp_f32_e32 v158, v66
	v_exp_f32_e32 v159, v67
	v_exp_f32_e32 v160, v68
	v_exp_f32_e32 v161, v69
	v_exp_f32_e32 v162, v70
	v_exp_f32_e32 v163, v71
	v_exp_f32_e32 v214, v72
	v_exp_f32_e32 v215, v73
	v_exp_f32_e32 v216, v74
	v_exp_f32_e32 v217, v75
	v_exp_f32_e32 v218, v76
	v_exp_f32_e32 v219, v77
	v_exp_f32_e32 v220, v78
	v_exp_f32_e32 v221, v79
	s_nop 0
	v_add_f32_e32 v253, v157, v156
	v_add_f32_e32 v253, v158, v253
	v_add_f32_e32 v253, v159, v253
	v_add_f32_e32 v253, v160, v253
	v_add_f32_e32 v253, v161, v253
	v_add_f32_e32 v253, v162, v253
	v_add_f32_e32 v253, v163, v253
	v_add_f32_e32 v253, v214, v253
	v_add_f32_e32 v253, v215, v253
	v_add_f32_e32 v253, v216, v253
	v_add_f32_e32 v253, v217, v253
	v_add_f32_e32 v253, v218, v253
	v_add_f32_e32 v253, v219, v253
	v_add_f32_e32 v253, v220, v253
	v_add_f32_e32 v192, v221, v253
	v_cvt_pk_bf16_f32 v144, v156, v157
	v_cvt_pk_bf16_f32 v145, v158, v159
	v_cvt_pk_bf16_f32 v146, v160, v161
	v_cvt_pk_bf16_f32 v147, v162, v163
	v_cvt_pk_bf16_f32 v148, v214, v215
	v_cvt_pk_bf16_f32 v149, v216, v217
	v_cvt_pk_bf16_f32 v150, v218, v219
	v_cvt_pk_bf16_f32 v151, v220, v221
.LBB0_167:
	s_add_i32 s9, s83, 0
	s_add_i32 s8, s37, -1
	s_add_i32 s100, s9, 0x4400
	v_add_u32_e32 v64, s9, v175
	s_waitcnt lgkmcnt(0)
	s_barrier
	s_waitcnt vmcnt(3)
	ds_write_b128 v64, v[116:119]
	s_waitcnt vmcnt(2)
	ds_write_b128 v64, v[120:123] offset:8704
	v_add_u32_e32 v64, s100, v184
	s_min_u32 s8, s8, 60
	s_waitcnt vmcnt(0)
	v_perm_b32 v65, v124, v112, s66
	v_perm_b32 v66, v124, v112, s67
	s_lshl_b32 s8, s8, 19
	ds_write2_b32 v64, v65, v66 offset1:32
	v_add_u32_e32 v65, s100, v185
	s_add_u32 s8, s30, s8
	v_perm_b32 v66, v125, v113, s66
	v_perm_b32 v67, v125, v113, s67
	s_addc_u32 s9, s31, 0
	ds_write2_b32 v65, v66, v67 offset0:64 offset1:96
	v_perm_b32 v66, v126, v114, s66
	v_perm_b32 v67, v126, v114, s67
	s_add_u32 s8, s8, 0x180000
	ds_write2_b32 v64, v66, v67 offset0:128 offset1:160
	v_perm_b32 v64, v127, v115, s66
	v_perm_b32 v66, v127, v115, s67
	s_addc_u32 s9, s9, 0
	ds_write2_b32 v65, v64, v66 offset0:192 offset1:224
	global_load_dwordx4 v[116:119], v254, s[8:9]
	global_load_dwordx4 v[124:127], v169, s[8:9]
	global_load_dwordx4 v[112:115], v173, s[8:9]
	global_load_dwordx4 v[120:123], v171, s[8:9]
	s_cmp_lg_u64 s[78:79], 0
	s_cselect_b32 s100, s69, 0x19800
	s_cmp_lg_u32 s100, s6
	s_cbranch_scc0 .Lda_bcskip2
	v_mov_b32_e32 v250, 0x18c00
	ds_read_b32 v251, v250
	ds_read_b32 v250, v250 offset:1024
	s_waitcnt lgkmcnt(0)
	v_sub_f32_e32 v250, v250, v251
	v_add_f32_e32 v232, v232, v250
	v_add_f32_e32 v233, v233, v250
	v_add_f32_e32 v234, v234, v250
	v_add_f32_e32 v235, v235, v250
	v_add_f32_e32 v236, v236, v250
	v_add_f32_e32 v237, v237, v250
	v_add_f32_e32 v238, v238, v250
	v_add_f32_e32 v239, v239, v250
	v_add_f32_e32 v240, v240, v250
	v_add_f32_e32 v241, v241, v250
	v_add_f32_e32 v242, v242, v250
	v_add_f32_e32 v243, v243, v250
	v_add_f32_e32 v244, v244, v250
	v_add_f32_e32 v245, v245, v250
	v_add_f32_e32 v246, v246, v250
	v_add_f32_e32 v247, v247, v250

; __device__ __forceinline__ void da_unit(LAS unsigned char* lds, const bf16_t* __restrict__ proj, bf16_t* __restrict__ y, int unit,
;                                         const float* __restrict__ t5, float lam, float one_m_li, const float* __restrict__ subg) {
;     ...
;         DA_STEP(sb, sa, pc0, pc1, pp0, pp1, lds + bcur, 0, lds + bnext, 0, j * 64 + 32, lds + bcur, 1);
;         bprev = bcur; bcur = bnext; bnext = bnn; bnn = bprev; near = near1; bc = bc1; dtoff = dtoff1;
.LBB0_172:
	s_and_b64 s[6:7], s[78:79], exec
	s_cselect_b32 s6, s69, 0x19800
	s_cmp_gt_u32 s81, s97
	s_cselect_b64 s[78:79], -1, 0
	s_and_b64 s[8:9], s[78:79], exec
	s_cselect_b32 s7, 0x400, 0
	s_add_i32 s7, s7, 0
	s_add_i32 s7, s7, 0x18c00
	s_cmp_gt_i32 s85, s40
	s_cselect_b64 s[8:9], -1, 0
	s_add_i32 s7, s86, 0xffffffa1
	s_cmpk_gt_i32 s7, 0x7f
	s_cselect_b64 s[88:89], -1, 0
	s_or_b64 s[8:9], s[8:9], s[88:89]
	s_and_b64 vcc, exec, s[8:9]
	s_cbranch_vccnz .LBB0_174
	v_add_u32_e32 v80, s6, v189
	v_add_u32_e32 v88, 0x600, v80
	v_add_u32_e32 v90, 0x608, v80
	v_add_u32_e32 v92, 0x620, v80
	v_add_u32_e32 v94, 0x628, v80
	v_add_u32_e32 v81, 0x640, v80
	v_add_u32_e32 v82, 0x648, v80
	v_add_u32_e32 v84, 0x660, v80
	v_add_u32_e32 v86, 0x668, v80
	ds_read2_b32 v[80:81], v81 offset1:1
	ds_read2_b32 v[82:83], v82 offset1:1
	ds_read2_b32 v[84:85], v84 offset1:1
	ds_read2_b32 v[86:87], v86 offset1:1
	ds_read2_b32 v[88:89], v88 offset1:1
	ds_read2_b32 v[90:91], v90 offset1:1
	ds_read2_b32 v[92:93], v92 offset1:1
	ds_read2_b32 v[94:95], v94 offset1:1
	s_waitcnt lgkmcnt(4)
	v_pk_add_f32 v[78:79], v[78:79], v[86:87]
	v_pk_add_f32 v[76:77], v[76:77], v[84:85]
	v_pk_add_f32 v[74:75], v[74:75], v[82:83]
	v_pk_add_f32 v[72:73], v[72:73], v[80:81]
	s_waitcnt lgkmcnt(0)
	v_pk_add_f32 v[70:71], v[70:71], v[94:95]
	v_pk_add_f32 v[68:69], v[68:69], v[92:93]
	v_pk_add_f32 v[66:67], v[66:67], v[90:91]
	v_pk_add_f32 v[64:65], v[64:65], v[88:89]
.LBB0_174:
	ds_read_b128 v[80:83], v178
	ds_read_b128 v[84:87], v155 offset:4096
	ds_read_b128 v[88:91], v178 offset:8192
	ds_read_b128 v[92:95], v155 offset:12288
	v_add_f32_e32 v192, v190, v192
	s_waitcnt lgkmcnt(7)
	v_mfma_f32_32x32x16_bf16 v[48:63], v[132:135], v[144:147], v[48:63]
	v_exp_f32_e32 v156, v64
	v_exp_f32_e32 v157, v65
	s_waitcnt lgkmcnt(6)
	v_mfma_f32_32x32x16_bf16 v[32:47], v[128:131], v[144:147], v[32:47]
	v_exp_f32_e32 v158, v66
	v_exp_f32_e32 v159, v67
	v_add_f32_e32 v253, v157, v156
	s_waitcnt lgkmcnt(5)
	v_mfma_f32_32x32x16_bf16 v[16:31], v[136:139], v[144:147], v[16:31]
	v_exp_f32_e32 v160, v68
	v_exp_f32_e32 v161, v69
	v_add_f32_e32 v253, v158, v253
	v_add_f32_e32 v253, v159, v253
	s_waitcnt lgkmcnt(4)
	v_mfma_f32_32x32x16_bf16 v[0:15], v[140:143], v[144:147], v[0:15]
	s_add_i32 s7, s84, 0
	s_add_i32 s8, s36, s7
	v_add3_u32 v128, s8, v186, v174
	ds_read_b128 v[144:147], v128 offset:8704
	ds_read_b128 v[198:201], v128 offset:8736
	ds_read_b128 v[224:227], v128 offset:8768
	ds_read_b128 v[228:231], v128 offset:8800
	v_exp_f32_e32 v162, v70
	v_exp_f32_e32 v163, v71
	v_add_f32_e32 v253, v160, v253
	v_add_f32_e32 v253, v161, v253
	s_waitcnt lgkmcnt(7)
	v_mfma_f32_32x32x16_bf16 v[48:63], v[80:83], v[148:151], v[48:63]
	v_add_u32_e32 v190, s7, v188
	v_xor_b32_e32 v191, 64, v190
	ds_read_b128 v[128:131], v190
	ds_read_b128 v[132:135], v191 offset:4096
	ds_read_b128 v[136:139], v190 offset:8192
	ds_read_b128 v[140:143], v191 offset:12288
	v_exp_f32_e32 v214, v72
	v_exp_f32_e32 v215, v73
	v_add_f32_e32 v253, v162, v253
	v_add_f32_e32 v253, v163, v253
	s_waitcnt lgkmcnt(10)
	v_mfma_f32_32x32x16_bf16 v[32:47], v[84:87], v[148:151], v[32:47]
	v_exp_f32_e32 v216, v74
	v_exp_f32_e32 v217, v75
	v_add_f32_e32 v253, v214, v253
	v_add_f32_e32 v253, v215, v253
	s_waitcnt lgkmcnt(9)
	v_mfma_f32_32x32x16_bf16 v[16:31], v[88:91], v[148:151], v[16:31]
	v_exp_f32_e32 v218, v76
	v_exp_f32_e32 v219, v77
	v_add_f32_e32 v253, v216, v253
	v_add_f32_e32 v253, v217, v253
	s_waitcnt lgkmcnt(8)
	v_mfma_f32_32x32x16_bf16 v[0:15], v[92:95], v[148:151], v[0:15]
	v_exp_f32_e32 v220, v78
	v_exp_f32_e32 v221, v79
	v_add_f32_e32 v253, v218, v253
	v_add_f32_e32 v253, v219, v253
	s_waitcnt lgkmcnt(7)
	v_mfma_f32_32x32x16_bf16 v[80:95], v[144:147], v[104:107], v[232:247]
	v_add_f32_e32 v253, v220, v253
	v_cvt_pk_bf16_f32 v148, v214, v215
	v_cvt_pk_bf16_f32 v149, v216, v217
	s_waitcnt lgkmcnt(6)
	v_mfma_f32_32x32x16_bf16 v[80:95], v[198:201], v[96:99], v[80:95]
	v_cvt_pk_bf16_f32 v150, v218, v219
	v_cvt_pk_bf16_f32 v151, v220, v221
	s_waitcnt lgkmcnt(5)
	v_mfma_f32_32x32x16_bf16 v[80:95], v[224:227], v[100:103], v[80:95]
	v_cvt_pk_bf16_f32 v144, v156, v157
	v_cvt_pk_bf16_f32 v145, v158, v159
	s_waitcnt lgkmcnt(4)
	v_mfma_f32_32x32x16_bf16 v[80:95], v[228:231], v[108:111], v[80:95]
	v_add_f32_e32 v193, v221, v253
	v_cvt_pk_bf16_f32 v146, v160, v161
	v_cvt_pk_bf16_f32 v147, v162, v163
	v_cmp_ngt_f32_e32 vcc, s68, v193
	s_cbranch_vccz .LBB0_177
	v_max3_f32 v250, v64, v65, v66
	v_max3_f32 v251, v67, v68, v69
	v_max3_f32 v250, v250, v70, v71
	v_max3_f32 v251, v251, v72, v73
	v_max3_f32 v250, v250, v74, v75
	v_max3_f32 v251, v251, v76, v77
	v_max3_f32 v250, v250, v78, v79
	v_max_f32_e32 v250, v250, v251
	v_mov_b32_e32 v251, v250
	s_nop 1
	v_permlane32_swap_b32_e32 v250, v251
	v_max_f32_e32 v250, v250, v251
	v_cmp_lt_f32_e32 vcc, v154, v250
	s_cbranch_vccz .LBB0_177
; #define DA_LOAD(j) do { const bf16_t* t_ = kvbase + (size_t)(j) * 64 * 4096; kreg0 = *(const u32x4*)(t_ + kgo); kreg1 = *(const u32x4*)(t_ + (kgo + 32u * 4096u)); vreg0 = *(const u32x4*)(t_ + vgo); vreg1 = *(const u32x4*)(t_ + (vgo + 4096u)); } while (0)
; __device__ __forceinline__ void da_unit(LAS unsigned char* lds, const bf16_t* __restrict__ proj, bf16_t* __restrict__ y, int unit,
;                                         const float* __restrict__ t5, float lam, float one_m_li, const float* __restrict__ subg) {
;     ...
; #pragma unroll 2
;     for (int j = 0; j < 64; ++j) {
;         const int j1 = j + 1;
;         const bool near1 = (64 * j1 + 63 >= qblk - 128) && (64 * j1 <= qblk + 255);
;         const float bc1 = tbl[(64 * j1 > qblk) ? 256 : 0]; const int dtoff1 = (64 * j1 > qblk) ? DA_DR_OFF : DA_DL_OFF;
;         DA_STEP(sa, sb, pp0, pp1, pc0, pc1, lds + bprev, 1, lds + bcur, 1, j * 64, lds + bcur, 0);
;         __syncthreads();
;         DA_STORE(lds + bnn); { const int jl = j + 3 < 64 ? j + 3 : 63; DA_LOAD(jl); }
	s_nop 1
	v_cndmask_b32_e32 v250, 0, v250, vcc
	v_sub_f32_e32 v251, 0, v250
	v_exp_f32_e32 v251, v251
	s_nop 0
	v_mul_f32_e32 v0, v251, v0
	v_mul_f32_e32 v1, v251, v1
	v_mul_f32_e32 v2, v251, v2
	v_mul_f32_e32 v3, v251, v3
	v_mul_f32_e32 v4, v251, v4
	v_mul_f32_e32 v5, v251, v5
	v_mul_f32_e32 v6, v251, v6
	v_mul_f32_e32 v7, v251, v7
	v_mul_f32_e32 v8, v251, v8
	v_mul_f32_e32 v9, v251, v9
	v_mul_f32_e32 v10, v251, v10
	v_mul_f32_e32 v11, v251, v11
	v_mul_f32_e32 v12, v251, v12
	v_mul_f32_e32 v13, v251, v13
	v_mul_f32_e32 v14, v251, v14
	v_mul_f32_e32 v15, v251, v15
	v_mul_f32_e32 v16, v251, v16
	v_mul_f32_e32 v17, v251, v17
	v_mul_f32_e32 v18, v251, v18
	v_mul_f32_e32 v19, v251, v19
	v_mul_f32_e32 v20, v251, v20
	v_mul_f32_e32 v21, v251, v21
	v_mul_f32_e32 v22, v251, v22
	v_mul_f32_e32 v23, v251, v23
	v_mul_f32_e32 v24, v251, v24
	v_mul_f32_e32 v25, v251, v25
	v_mul_f32_e32 v26, v251, v26
	v_mul_f32_e32 v27, v251, v27
	v_mul_f32_e32 v28, v251, v28
	v_mul_f32_e32 v29, v251, v29
	v_mul_f32_e32 v30, v251, v30
	v_mul_f32_e32 v31, v251, v31
	v_mul_f32_e32 v32, v251, v32
	v_mul_f32_e32 v33, v251, v33
	v_mul_f32_e32 v34, v251, v34
	v_mul_f32_e32 v35, v251, v35
	v_mul_f32_e32 v36, v251, v36
	v_mul_f32_e32 v37, v251, v37
	v_mul_f32_e32 v38, v251, v38
	v_mul_f32_e32 v39, v251, v39
	v_mul_f32_e32 v40, v251, v40
	v_mul_f32_e32 v41, v251, v41
	v_mul_f32_e32 v42, v251, v42
	v_mul_f32_e32 v43, v251, v43
	v_mul_f32_e32 v44, v251, v44
	v_mul_f32_e32 v45, v251, v45
	v_mul_f32_e32 v46, v251, v46
	v_mul_f32_e32 v47, v251, v47
	v_mul_f32_e32 v48, v251, v48
	v_mul_f32_e32 v49, v251, v49
	v_mul_f32_e32 v50, v251, v50
	v_mul_f32_e32 v51, v251, v51
	v_mul_f32_e32 v52, v251, v52
	v_mul_f32_e32 v53, v251, v53
	v_mul_f32_e32 v54, v251, v54
	v_mul_f32_e32 v55, v251, v55
	v_mul_f32_e32 v56, v251, v56
	v_mul_f32_e32 v57, v251, v57
	v_mul_f32_e32 v58, v251, v58
	v_mul_f32_e32 v59, v251, v59
	v_mul_f32_e32 v60, v251, v60
	v_mul_f32_e32 v61, v251, v61
	v_mul_f32_e32 v62, v251, v62
	v_mul_f32_e32 v63, v251, v63
	v_mul_f32_e32 v192, v251, v192
	v_sub_f32_e32 v64, v64, v250
	v_sub_f32_e32 v65, v65, v250
	v_sub_f32_e32 v66, v66, v250
	v_sub_f32_e32 v67, v67, v250
	v_sub_f32_e32 v68, v68, v250
	v_sub_f32_e32 v69, v69, v250
	v_sub_f32_e32 v70, v70, v250
	v_sub_f32_e32 v71, v71, v250
	v_sub_f32_e32 v72, v72, v250
	v_sub_f32_e32 v73, v73, v250
	v_sub_f32_e32 v74, v74, v250
	v_sub_f32_e32 v75, v75, v250
	v_sub_f32_e32 v76, v76, v250
	v_sub_f32_e32 v77, v77, v250
	v_sub_f32_e32 v78, v78, v250
	v_sub_f32_e32 v79, v79, v250
	v_sub_f32_e32 v80, v80, v250
	v_sub_f32_e32 v81, v81, v250
	v_sub_f32_e32 v82, v82, v250
	v_sub_f32_e32 v83, v83, v250
	v_sub_f32_e32 v84, v84, v250
	v_sub_f32_e32 v85, v85, v250
	v_sub_f32_e32 v86, v86, v250
	v_sub_f32_e32 v87, v87, v250
	v_sub_f32_e32 v88, v88, v250
	v_sub_f32_e32 v89, v89, v250
	v_sub_f32_e32 v90, v90, v250
	v_sub_f32_e32 v91, v91, v250
	v_sub_f32_e32 v92, v92, v250
	v_sub_f32_e32 v93, v93, v250
	v_sub_f32_e32 v94, v94, v250
	v_sub_f32_e32 v95, v95, v250
	v_sub_f32_e32 v232, v232, v250
	v_sub_f32_e32 v233, v233, v250
	v_sub_f32_e32 v234, v234, v250
	v_sub_f32_e32 v235, v235, v250
	v_sub_f32_e32 v236, v236, v250
	v_sub_f32_e32 v237, v237, v250
	v_sub_f32_e32 v238, v238, v250
	v_sub_f32_e32 v239, v239, v250
	v_sub_f32_e32 v240, v240, v250
	v_sub_f32_e32 v241, v241, v250
	v_sub_f32_e32 v242, v242, v250
	v_sub_f32_e32 v243, v243, v250
	v_sub_f32_e32 v244, v244, v250
	v_sub_f32_e32 v245, v245, v250
	v_sub_f32_e32 v246, v246, v250
	v_sub_f32_e32 v247, v247, v250
	v_exp_f32_e32 v156, v64
	v_exp_f32_e32 v157, v65
	v_exp_f32_e32 v158, v66
	v_exp_f32_e32 v159, v67
	v_exp_f32_e32 v160, v68
	v_exp_f32_e32 v161, v69
	v_exp_f32_e32 v162, v70
	v_exp_f32_e32 v163, v71
	v_exp_f32_e32 v214, v72
	v_exp_f32_e32 v215, v73
	v_exp_f32_e32 v216, v74
	v_exp_f32_e32 v217, v75
	v_exp_f32_e32 v218, v76
	v_exp_f32_e32 v219, v77
	v_exp_f32_e32 v220, v78
	v_exp_f32_e32 v221, v79
	s_nop 0
	v_add_f32_e32 v253, v157, v156
	v_add_f32_e32 v253, v158, v253
	v_add_f32_e32 v253, v159, v253
	v_add_f32_e32 v253, v160, v253
	v_add_f32_e32 v253, v161, v253
	v_add_f32_e32 v253, v162, v253
	v_add_f32_e32 v253, v163, v253
	v_add_f32_e32 v253, v214, v253
	v_add_f32_e32 v253, v215, v253
	v_add_f32_e32 v253, v216, v253
	v_add_f32_e32 v253, v217, v253
	v_add_f32_e32 v253, v218, v253
	v_add_f32_e32 v253, v219, v253
	v_add_f32_e32 v253, v220, v253
	v_add_f32_e32 v193, v221, v253
	v_cvt_pk_bf16_f32 v144, v156, v157
	v_cvt_pk_bf16_f32 v145, v158, v159
	v_cvt_pk_bf16_f32 v146, v160, v161
	v_cvt_pk_bf16_f32 v147, v162, v163
	v_cvt_pk_bf16_f32 v148, v214, v215
	v_cvt_pk_bf16_f32 v149, v216, v217
	v_cvt_pk_bf16_f32 v150, v218, v219
	v_cvt_pk_bf16_f32 v151, v220, v221
.LBB0_177:
	s_add_i32 s100, s87, 0x4400
	v_add_u32_e32 v64, s87, v175
	s_waitcnt lgkmcnt(0)
	s_barrier
	s_waitcnt vmcnt(3)
	ds_write_b128 v64, v[116:119]
	s_waitcnt vmcnt(2)
	ds_write_b128 v64, v[124:127] offset:8704
	v_add_u32_e32 v64, s100, v184
	s_min_u32 s7, s37, 60
	s_waitcnt vmcnt(0)
	v_perm_b32 v65, v120, v112, s66
	v_perm_b32 v66, v120, v112, s67
	s_lshl_b32 s7, s7, 19
	ds_write2_b32 v64, v65, v66 offset1:32
	v_add_u32_e32 v65, s100, v185
	s_add_u32 s7, s30, s7
	v_perm_b32 v66, v121, v113, s66
	v_perm_b32 v67, v121, v113, s67
	s_addc_u32 s9, s31, 0
	ds_write2_b32 v65, v66, v67 offset0:64 offset1:96
	v_perm_b32 v66, v122, v114, s66
	v_perm_b32 v67, v122, v114, s67
	s_add_u32 s8, s7, 0x180000
	ds_write2_b32 v64, v66, v67 offset0:128 offset1:160
	v_perm_b32 v64, v123, v115, s66
	v_perm_b32 v66, v123, v115, s67
	s_addc_u32 s9, s9, 0
	ds_write2_b32 v65, v64, v66 offset0:192 offset1:224
	global_load_dwordx4 v[116:119], v254, s[8:9]
	global_load_dwordx4 v[120:123], v169, s[8:9]
	global_load_dwordx4 v[112:115], v173, s[8:9]
	global_load_dwordx4 v[124:127], v171, s[8:9]
	s_cmp_lg_u64 s[78:79], 0
	s_cselect_b32 s100, s69, 0x19800
	s_cmp_lg_u32 s100, s6
	s_cbranch_scc0 .Lda_bcskip4
	v_mov_b32_e32 v250, 0x18c00
	ds_read_b32 v251, v250
	ds_read_b32 v250, v250 offset:1024
	s_waitcnt lgkmcnt(0)
	v_sub_f32_e32 v250, v250, v251
	v_add_f32_e32 v232, v232, v250
	v_add_f32_e32 v233, v233, v250
	v_add_f32_e32 v234, v234, v250
	v_add_f32_e32 v235, v235, v250
	v_add_f32_e32 v236, v236, v250
	v_add_f32_e32 v237, v237, v250
	v_add_f32_e32 v238, v238, v250
	v_add_f32_e32 v239, v239, v250
	v_add_f32_e32 v240, v240, v250
	v_add_f32_e32 v241, v241, v250
	v_add_f32_e32 v242, v242, v250
	v_add_f32_e32 v243, v243, v250
	v_add_f32_e32 v244, v244, v250
	v_add_f32_e32 v245, v245, v250
	v_add_f32_e32 v246, v246, v250
	v_add_f32_e32 v247, v247, v250
